# v42 + early L1 invalidate in P5 counter wait and P4 panel-stats exchange
# baseline (speedup 1.0000x reference)
.LBB0_3616:
	s_or_b64 exec, exec, s[20:21]
	s_cmp_gt_u32 s38, 63
	s_cbranch_scc1 .LBB0_3633
	buffer_inv sc1
	s_memrealtime s[20:21]
	s_lshl_b32 s22, s16, 6
	s_ashr_i32 s23, s22, 31
	s_lshl_b64 s[22:23], s[22:23], 2
	s_add_u32 s22, s13, s22
	s_addc_u32 s23, s17, s23
	v_mov_b32_e32 v131, 0
	v_mov_b64_e32 v[128:129], 0x1e8481
	s_branch .LBB0_3620

.LBB0_3630:
	s_waitcnt vmcnt(0)
	s_and_b64 exec, exec, s[2:3]
	v_cndmask_b32_e64 v128, 0, 1, s[14:15]
	v_mov_b32_e32 v129, 0
	ds_write_b32 v129, v128 offset:10240

.LBB0_3641:
	v_mov_b32_e32 v49, 0
	s_waitcnt lgkmcnt(0)
	buffer_inv sc1
	global_load_dword v51, v49, s[2:3] offset:512 sc1
	s_movk_i32 s11, 0xff
	s_waitcnt vmcnt(0)
	v_cmp_lt_u32_e32 vcc, s11, v51
	s_cbranch_vccnz .LBB0_3654
	s_add_u32 s16, s2, 0x4200
	s_addc_u32 s17, s3, 0
	s_mov_b32 s25, 1
	s_branch .LBB0_3644

.LBB0_3654:
	s_waitcnt vmcnt(0)
.LBB0_3655:
	s_or_b64 exec, exec, s[14:15]
	s_andn2_b64 vcc, exec, s[12:13]
	s_waitcnt lgkmcnt(0)
	s_barrier
	s_cbranch_vccnz .LBB0_3682
	v_mbcnt_lo_u32_b32 v49, -1, 0
	v_mbcnt_hi_u32_b32 v49, -1, v49
	v_and_b32_e32 v51, 64, v49
	v_add_u32_e32 v51, 64, v51
	v_xor_b32_e32 v52, 1, v49
	v_cmp_lt_i32_e32 vcc, v52, v51
	s_mov_b32 s11, 0
	s_mov_b32 s14, 0x3f9837f0
	v_cndmask_b32_e32 v52, v49, v52, vcc
	v_lshlrev_b32_e32 v86, 2, v52
	v_xor_b32_e32 v52, 2, v49
	v_cmp_lt_i32_e32 vcc, v52, v51
	v_mov_b32_e32 v92, 0x3727c5ac
	s_mov_b32 s15, 0xf800000
	v_cndmask_b32_e32 v52, v49, v52, vcc
	v_lshlrev_b32_e32 v87, 2, v52
	v_xor_b32_e32 v52, 4, v49
	v_cmp_lt_i32_e32 vcc, v52, v51
	v_mov_b32_e32 v93, 0x260
	s_nop 0
	v_cndmask_b32_e32 v52, v49, v52, vcc
	v_lshlrev_b32_e32 v88, 2, v52
	v_xor_b32_e32 v52, 8, v49
	v_cmp_lt_i32_e32 vcc, v52, v51
	s_nop 1
	v_cndmask_b32_e32 v52, v49, v52, vcc
	v_lshlrev_b32_e32 v89, 2, v52
	v_xor_b32_e32 v52, 16, v49
	v_cmp_lt_i32_e32 vcc, v52, v51
	s_nop 1
	v_cndmask_b32_e32 v52, v49, v52, vcc
	v_lshlrev_b32_e32 v90, 2, v52
	v_xor_b32_e32 v52, 32, v49
	v_cmp_lt_i32_e32 vcc, v52, v51
	s_nop 1
	v_cndmask_b32_e32 v49, v49, v52, vcc
	v_lshlrev_b32_e32 v91, 2, v49
	v_mov_b32_e32 v49, 0
	v_lshl_add_u64 v[76:77], s[4:5], 0, v[48:49]
	s_add_u32 s4, s0, 0x4000800
	s_addc_u32 s5, s1, 0
	s_ashr_i32 s1, s24, 31
	s_add_u32 s0, s96, s24
	s_addc_u32 s1, s97, s1
	s_lshl_b64 s[0:1], s[0:1], 12
	v_lshl_or_b32 v80, v50, 4, s0
	v_mov_b32_e32 v81, s1
	v_readlane_b32 s0, v254, 11
	v_readlane_b32 s1, v254, 12
	s_ashr_i32 s1, s0, 31
	v_lshl_add_u64 v[78:79], s[6:7], 0, v[48:49]
	s_lshl_b64 s[6:7], s[0:1], 12
	s_add_u32 s12, s2, 0x12e00800
	s_mov_b32 s16, s0
	s_addc_u32 s13, s3, 0
	s_branch .LBB0_3658
